# grid barrier: non-leader workgroups poll the cross-XCD release word (TOPGEN) directly instead of the per-XCD word their leader bumps afterwards (one hop less per barrier, 20 barriers)
# baseline (speedup 1.0000x reference)
.LBB0_38:
	s_or_b64 exec, exec, s[6:7]
	v_cvt_f32_u32_e32 v4, v2
	s_waitcnt vmcnt(0)
	v_readfirstlane_b32 s4, v3
	v_sub_u32_e32 v3, 0, v2
	v_rcp_iflag_f32_e32 v4, v4
	v_add_u32_e32 v5, s4, v1
	v_mul_f32_e32 v4, 0x4f7ffffe, v4
	v_cvt_u32_f32_e32 v4, v4
	v_mul_lo_u32 v1, v3, v4
	v_mul_hi_u32 v1, v4, v1
	v_add_u32_e32 v1, v4, v1
	v_mul_hi_u32 v1, v5, v1
	v_mul_lo_u32 v3, v1, v2
	v_sub_u32_e32 v3, v5, v3
	v_add_u32_e32 v4, 1, v1
	v_cmp_ge_u32_e32 vcc, v3, v2
	s_nop 1
	v_cndmask_b32_e32 v1, v1, v4, vcc
	v_sub_u32_e32 v4, v3, v2
	v_cndmask_b32_e32 v3, v3, v4, vcc
	v_add_u32_e32 v4, 1, v1
	v_cmp_ge_u32_e32 vcc, v3, v2
	v_add_u32_e32 v3, 1, v5
	s_nop 0
	v_cndmask_b32_e32 v1, v1, v4, vcc
	v_mul_lo_u32 v4, v2, v1
	v_add_u32_e32 v2, v4, v2
	v_cmp_ne_u32_e32 vcc, v3, v2
	s_and_saveexec_b64 s[4:5], vcc
	s_xor_b64 s[4:5], exec, s[4:5]
	s_cbranch_execz .LBB0_52
	s_waitcnt lgkmcnt(0)
	s_add_u32 s12, s94, 0x2b500
	s_addc_u32 s13, s95, 0
	v_mov_b32_e32 v0, 0
	global_load_dword v0, v0, s[12:13] sc1
	s_waitcnt vmcnt(0)
	v_cmp_eq_u32_e32 vcc, v0, v1
	s_and_saveexec_b64 s[6:7], vcc
	s_cbranch_execz .LBB0_51
	s_add_u32 s10, s94, 0x28200
	s_addc_u32 s11, s95, 0
	s_mov_b32 s24, 1
	s_mov_b64 s[14:15], 0
	v_mov_b32_e32 v0, 0
	s_branch .LBB0_42

.LBB0_124:
	s_or_b64 exec, exec, s[8:9]
	v_cvt_f32_u32_e32 v4, v2
	s_waitcnt vmcnt(0)
	v_readfirstlane_b32 s6, v3
	v_sub_u32_e32 v3, 0, v2
	v_rcp_iflag_f32_e32 v4, v4
	v_add_u32_e32 v5, s6, v1
	v_mul_f32_e32 v4, 0x4f7ffffe, v4
	v_cvt_u32_f32_e32 v4, v4
	v_mul_lo_u32 v1, v3, v4
	v_mul_hi_u32 v1, v4, v1
	v_add_u32_e32 v1, v4, v1
	v_mul_hi_u32 v1, v5, v1
	v_mul_lo_u32 v3, v1, v2
	v_sub_u32_e32 v3, v5, v3
	v_add_u32_e32 v4, 1, v1
	v_cmp_ge_u32_e32 vcc, v3, v2
	s_nop 1
	v_cndmask_b32_e32 v1, v1, v4, vcc
	v_sub_u32_e32 v4, v3, v2
	v_cndmask_b32_e32 v3, v3, v4, vcc
	v_add_u32_e32 v4, 1, v1
	v_cmp_ge_u32_e32 vcc, v3, v2
	v_add_u32_e32 v3, 1, v5
	s_nop 0
	v_cndmask_b32_e32 v1, v1, v4, vcc
	v_mul_lo_u32 v4, v2, v1
	v_add_u32_e32 v2, v4, v2
	v_cmp_ne_u32_e32 vcc, v3, v2
	s_and_saveexec_b64 s[6:7], vcc
	s_xor_b64 s[6:7], exec, s[6:7]
	s_cbranch_execz .LBB0_138
	s_waitcnt lgkmcnt(0)
	s_add_u32 s12, s94, 0x2b500
	s_addc_u32 s13, s95, 0
	v_mov_b32_e32 v0, 0
	global_load_dword v0, v0, s[12:13] sc1
	s_waitcnt vmcnt(0)
	v_cmp_eq_u32_e32 vcc, v0, v1
	s_and_saveexec_b64 s[8:9], vcc
	s_cbranch_execz .LBB0_137
	s_add_u32 s10, s94, 0x28200
	s_addc_u32 s11, s95, 0
	s_mov_b32 s24, 1
	s_mov_b64 s[14:15], 0
	v_mov_b32_e32 v0, 0
	s_branch .LBB0_128

.LBB0_412:
	s_or_b64 exec, exec, s[6:7]
	v_cvt_f32_u32_e32 v4, v2
	s_waitcnt vmcnt(0)
	v_readfirstlane_b32 s4, v3
	v_sub_u32_e32 v3, 0, v2
	v_rcp_iflag_f32_e32 v4, v4
	v_add_u32_e32 v5, s4, v1
	v_mul_f32_e32 v4, 0x4f7ffffe, v4
	v_cvt_u32_f32_e32 v4, v4
	v_mul_lo_u32 v1, v3, v4
	v_mul_hi_u32 v1, v4, v1
	v_add_u32_e32 v1, v4, v1
	v_mul_hi_u32 v1, v5, v1
	v_mul_lo_u32 v3, v1, v2
	v_sub_u32_e32 v3, v5, v3
	v_add_u32_e32 v4, 1, v1
	v_cmp_ge_u32_e32 vcc, v3, v2
	s_nop 1
	v_cndmask_b32_e32 v1, v1, v4, vcc
	v_sub_u32_e32 v4, v3, v2
	v_cndmask_b32_e32 v3, v3, v4, vcc
	v_add_u32_e32 v4, 1, v1
	v_cmp_ge_u32_e32 vcc, v3, v2
	v_add_u32_e32 v3, 1, v5
	s_nop 0
	v_cndmask_b32_e32 v1, v1, v4, vcc
	v_mul_lo_u32 v4, v2, v1
	v_add_u32_e32 v2, v4, v2
	v_cmp_ne_u32_e32 vcc, v3, v2
	s_and_saveexec_b64 s[4:5], vcc
	s_xor_b64 s[4:5], exec, s[4:5]
	s_cbranch_execz .LBB0_426
	s_waitcnt lgkmcnt(0)
	s_add_u32 s10, s94, 0x2b500
	s_addc_u32 s11, s95, 0
	v_mov_b32_e32 v0, 0
	global_load_dword v0, v0, s[10:11] sc1
	s_waitcnt vmcnt(0)
	v_cmp_eq_u32_e32 vcc, v0, v1
	s_and_saveexec_b64 s[6:7], vcc
	s_cbranch_execz .LBB0_425
	s_add_u32 s8, s94, 0x28200
	s_addc_u32 s9, s95, 0
	s_mov_b32 s24, 1
	s_mov_b64 s[12:13], 0
	v_mov_b32_e32 v0, 0
	s_branch .LBB0_416

.LBB0_489:
	s_or_b64 exec, exec, s[6:7]
	v_cvt_f32_u32_e32 v4, v2
	s_waitcnt vmcnt(0)
	v_readfirstlane_b32 s4, v3
	v_sub_u32_e32 v3, 0, v2
	v_rcp_iflag_f32_e32 v4, v4
	v_add_u32_e32 v5, s4, v1
	v_mul_f32_e32 v4, 0x4f7ffffe, v4
	v_cvt_u32_f32_e32 v4, v4
	v_mul_lo_u32 v1, v3, v4
	v_mul_hi_u32 v1, v4, v1
	v_add_u32_e32 v1, v4, v1
	v_mul_hi_u32 v1, v5, v1
	v_mul_lo_u32 v3, v1, v2
	v_sub_u32_e32 v3, v5, v3
	v_add_u32_e32 v4, 1, v1
	v_cmp_ge_u32_e32 vcc, v3, v2
	s_nop 1
	v_cndmask_b32_e32 v1, v1, v4, vcc
	v_sub_u32_e32 v4, v3, v2
	v_cndmask_b32_e32 v3, v3, v4, vcc
	v_add_u32_e32 v4, 1, v1
	v_cmp_ge_u32_e32 vcc, v3, v2
	v_add_u32_e32 v3, 1, v5
	s_nop 0
	v_cndmask_b32_e32 v1, v1, v4, vcc
	v_mul_lo_u32 v4, v2, v1
	v_add_u32_e32 v2, v4, v2
	v_cmp_ne_u32_e32 vcc, v3, v2
	s_and_saveexec_b64 s[4:5], vcc
	s_xor_b64 s[4:5], exec, s[4:5]
	s_cbranch_execz .LBB0_503
	s_waitcnt lgkmcnt(0)
	s_add_u32 s10, s94, 0x2b500
	s_addc_u32 s11, s95, 0
	v_mov_b32_e32 v0, 0
	global_load_dword v0, v0, s[10:11] sc1
	s_waitcnt vmcnt(0)
	v_cmp_eq_u32_e32 vcc, v0, v1
	s_and_saveexec_b64 s[6:7], vcc
	s_cbranch_execz .LBB0_502
	s_add_u32 s8, s94, 0x28200
	s_addc_u32 s9, s95, 0
	s_mov_b32 s24, 1
	s_mov_b64 s[14:15], 0
	v_mov_b32_e32 v0, 0
	s_branch .LBB0_493

.LBB0_698:
	s_or_b64 exec, exec, s[6:7]
	v_cvt_f32_u32_e32 v4, v2
	s_waitcnt vmcnt(0)
	v_readfirstlane_b32 s4, v3
	v_sub_u32_e32 v3, 0, v2
	v_rcp_iflag_f32_e32 v4, v4
	v_add_u32_e32 v5, s4, v1
	v_mul_f32_e32 v4, 0x4f7ffffe, v4
	v_cvt_u32_f32_e32 v4, v4
	v_mul_lo_u32 v1, v3, v4
	v_mul_hi_u32 v1, v4, v1
	v_add_u32_e32 v1, v4, v1
	v_mul_hi_u32 v1, v5, v1
	v_mul_lo_u32 v3, v1, v2
	v_sub_u32_e32 v3, v5, v3
	v_add_u32_e32 v4, 1, v1
	v_cmp_ge_u32_e32 vcc, v3, v2
	s_nop 1
	v_cndmask_b32_e32 v1, v1, v4, vcc
	v_sub_u32_e32 v4, v3, v2
	v_cndmask_b32_e32 v3, v3, v4, vcc
	v_add_u32_e32 v4, 1, v1
	v_cmp_ge_u32_e32 vcc, v3, v2
	v_add_u32_e32 v3, 1, v5
	s_nop 0
	v_cndmask_b32_e32 v1, v1, v4, vcc
	v_mul_lo_u32 v4, v2, v1
	v_add_u32_e32 v2, v4, v2
	v_cmp_ne_u32_e32 vcc, v3, v2
	s_and_saveexec_b64 s[4:5], vcc
	s_xor_b64 s[4:5], exec, s[4:5]
	s_cbranch_execz .LBB0_712
	s_waitcnt lgkmcnt(0)
	s_add_u32 s10, s94, 0x2b500
	s_addc_u32 s11, s95, 0
	v_mov_b32_e32 v0, 0
	global_load_dword v0, v0, s[10:11] sc1
	s_waitcnt vmcnt(0)
	v_cmp_eq_u32_e32 vcc, v0, v1
	s_and_saveexec_b64 s[6:7], vcc
	s_cbranch_execz .LBB0_711
	s_add_u32 s8, s94, 0x28200
	s_addc_u32 s9, s95, 0
	s_mov_b32 s22, 1
	s_mov_b64 s[12:13], 0
	v_mov_b32_e32 v0, 0
	s_branch .LBB0_702

.LBB0_895:
	s_or_b64 exec, exec, s[8:9]
	v_cvt_f32_u32_e32 v4, v2
	s_waitcnt vmcnt(0)
	v_readfirstlane_b32 s4, v3
	v_sub_u32_e32 v3, 0, v2
	v_rcp_iflag_f32_e32 v4, v4
	v_add_u32_e32 v5, s4, v1
	v_mul_f32_e32 v4, 0x4f7ffffe, v4
	v_cvt_u32_f32_e32 v4, v4
	v_mul_lo_u32 v1, v3, v4
	v_mul_hi_u32 v1, v4, v1
	v_add_u32_e32 v1, v4, v1
	v_mul_hi_u32 v1, v5, v1
	v_mul_lo_u32 v3, v1, v2
	v_sub_u32_e32 v3, v5, v3
	v_add_u32_e32 v4, 1, v1
	v_cmp_ge_u32_e32 vcc, v3, v2
	s_nop 1
	v_cndmask_b32_e32 v1, v1, v4, vcc
	v_sub_u32_e32 v4, v3, v2
	v_cndmask_b32_e32 v3, v3, v4, vcc
	v_add_u32_e32 v4, 1, v1
	v_cmp_ge_u32_e32 vcc, v3, v2
	v_add_u32_e32 v3, 1, v5
	s_nop 0
	v_cndmask_b32_e32 v1, v1, v4, vcc
	v_mul_lo_u32 v4, v2, v1
	v_add_u32_e32 v2, v4, v2
	v_cmp_ne_u32_e32 vcc, v3, v2
	s_and_saveexec_b64 s[4:5], vcc
	s_xor_b64 s[4:5], exec, s[4:5]
	s_cbranch_execz .LBB0_909
	s_waitcnt lgkmcnt(0)
	s_add_u32 s12, s94, 0x2b500
	s_addc_u32 s13, s95, 0
	v_mov_b32_e32 v0, 0
	global_load_dword v0, v0, s[12:13] sc1
	s_waitcnt vmcnt(0)
	v_cmp_eq_u32_e32 vcc, v0, v1
	s_and_saveexec_b64 s[8:9], vcc
	s_cbranch_execz .LBB0_908
	s_add_u32 s10, s94, 0x28200
	s_addc_u32 s11, s95, 0
	s_mov_b32 s24, 1
	s_mov_b64 s[14:15], 0
	v_mov_b32_e32 v0, 0
	s_branch .LBB0_899
